# attn: PV-block lgkmcnt waits merged to one per prefetched V group (inst1), row-max tree 21->17 ops
# speedup vs baseline: 1.0353x; 1.0045x over previous
.LBB0_861:
	v_max_f32_e32 v0, v144, v145
	v_max3_f32 v2, v147, v44, v45
	v_max3_f32 v0, v0, v146, v46
	v_max3_f32 v2, v2, v140, v141
	v_max3_f32 v0, v0, v47, v142
	v_max3_f32 v2, v2, v72, v73
	v_max3_f32 v0, v0, v143, v74
	v_max3_f32 v0, v0, v75, v2
	v_max_f32_e32 v2, v136, v137
	v_max3_f32 v3, v139, v92, v93
	v_max3_f32 v2, v2, v138, v94
	v_max3_f32 v3, v3, v132, v133
	v_max3_f32 v2, v2, v95, v134
	v_max3_f32 v3, v3, v112, v113
	v_max3_f32 v2, v2, v135, v114
	v_max3_f32 v2, v2, v115, v3
	v_max_f32_e32 v3, v0, v2
	v_cmp_lt_f32_e32 vcc, s74, v3
	s_cmp_lg_u64 vcc, 0
	s_cselect_b64 s[0:1], -1, 0
	s_cbranch_vccz .LBB0_863
	v_and_b32_e32 v148, 64, v212
	v_xor_b32_e32 v3, 16, v212
	v_add_u32_e32 v148, 64, v148
	v_cmp_lt_i32_e32 vcc, v3, v148
	v_xor_b32_e32 v149, 32, v212
	s_nop 0
	v_cndmask_b32_e32 v3, v212, v3, vcc
	v_lshlrev_b32_e32 v3, 2, v3
	ds_bpermute_b32 v150, v3, v0
	ds_bpermute_b32 v3, v3, v2
	v_cmp_lt_i32_e32 vcc, v149, v148
	v_max_f32_e32 v2, v2, v2
	v_max_f32_e32 v0, v0, v0
	v_cndmask_b32_e32 v148, v212, v149, vcc
	s_waitcnt lgkmcnt(0)
	v_max_f32_e32 v3, v3, v3
	v_lshlrev_b32_e32 v148, 2, v148
	v_max_f32_e32 v149, v150, v150
	v_max_f32_e32 v2, v2, v3
	v_max_f32_e32 v0, v0, v149
	ds_bpermute_b32 v3, v148, v2
	ds_bpermute_b32 v149, v148, v0
	s_waitcnt lgkmcnt(1)
	v_max_f32_e32 v3, v3, v3
	s_waitcnt lgkmcnt(0)
	v_max_f32_e32 v148, v149, v149
	v_max_f32_e32 v2, v2, v3
	v_max_f32_e32 v0, v0, v148
	v_cmp_lt_f32_e32 vcc, s74, v2
	s_nop 1
	v_cndmask_b32_e32 v3, 0, v2, vcc
	v_cmp_lt_f32_e32 vcc, s74, v0
	v_exp_f32_e64 v201, -v3
	v_sub_f32_e32 v136, v136, v3
	v_cndmask_b32_e32 v2, 0, v0, vcc
	v_exp_f32_e64 v200, -v2
	v_sub_f32_e32 v144, v144, v2
	v_sub_f32_e32 v145, v145, v2
	v_sub_f32_e32 v146, v146, v2
	v_sub_f32_e32 v147, v147, v2
	v_sub_f32_e32 v44, v44, v2
	v_sub_f32_e32 v45, v45, v2
	v_sub_f32_e32 v46, v46, v2
	v_sub_f32_e32 v47, v47, v2
	v_sub_f32_e32 v140, v140, v2
	v_sub_f32_e32 v141, v141, v2
	v_sub_f32_e32 v142, v142, v2
	v_sub_f32_e32 v143, v143, v2
	v_sub_f32_e32 v72, v72, v2
	v_sub_f32_e32 v73, v73, v2
	v_sub_f32_e32 v74, v74, v2
	v_sub_f32_e32 v75, v75, v2
	v_pk_add_f32 v[196:197], v[196:197], v[2:3]
	v_sub_f32_e32 v137, v137, v3
	v_sub_f32_e32 v138, v138, v3
	v_sub_f32_e32 v139, v139, v3
	v_sub_f32_e32 v92, v92, v3
	v_sub_f32_e32 v93, v93, v3
	v_sub_f32_e32 v94, v94, v3
	v_sub_f32_e32 v95, v95, v3
	v_sub_f32_e32 v132, v132, v3
	v_sub_f32_e32 v133, v133, v3
	v_sub_f32_e32 v134, v134, v3
	v_sub_f32_e32 v135, v135, v3
	v_sub_f32_e32 v112, v112, v3
	v_sub_f32_e32 v113, v113, v3
	v_sub_f32_e32 v114, v114, v3
	v_sub_f32_e32 v115, v115, v3
	v_pk_mul_f32 v[198:199], v[198:199], v[200:201]
.LBB0_863:
	ds_read_b64_tr_b16 v[148:149], v215 offset:17408
	ds_read_b64_tr_b16 v[152:153], v215 offset:17440
	ds_read_b64_tr_b16 v[156:157], v215 offset:17472
	ds_read_b64_tr_b16 v[160:161], v215 offset:17504
	ds_read_b64_tr_b16 v[150:151], v215 offset:22016
	ds_read_b64_tr_b16 v[154:155], v215 offset:22048
	ds_read_b64_tr_b16 v[158:159], v215 offset:22080
	ds_read_b64_tr_b16 v[162:163], v215 offset:22112
	v_exp_f32_e32 v2, v144
	s_waitcnt lgkmcnt(3)
	v_mfma_f32_16x16x32_bf16 v[164:167], v[36:39], v[148:151], v[128:131]
	v_exp_f32_e32 v222, v145
	v_mfma_f32_16x16x32_bf16 v[148:151], v[60:63], v[148:151], v[120:123]
	ds_read_b64_tr_b16 v[238:239], v215 offset:17536
	ds_read_b64_tr_b16 v[242:243], v215 offset:17568
	ds_read_b64_tr_b16 v[246:247], v215 offset:17600
	ds_read_b64_tr_b16 v[250:251], v215 offset:17632
	ds_read_b64_tr_b16 v[240:241], v215 offset:22144
	ds_read_b64_tr_b16 v[244:245], v215 offset:22176
	ds_read_b64_tr_b16 v[248:249], v215 offset:22208
	ds_read_b64_tr_b16 v[252:253], v215 offset:22240
	v_exp_f32_e32 v224, v146
	s_waitcnt lgkmcnt(10)
	v_mfma_f32_16x16x32_bf16 v[124:127], v[36:39], v[152:155], v[124:127]
	v_exp_f32_e32 v122, v147
	v_mfma_f32_16x16x32_bf16 v[152:155], v[60:63], v[152:155], v[108:111]
	v_exp_f32_e32 v226, v44
	s_waitcnt lgkmcnt(9)
	v_mfma_f32_16x16x32_bf16 v[116:119], v[36:39], v[156:159], v[116:119]
	v_exp_f32_e32 v110, v45
	v_mfma_f32_16x16x32_bf16 v[168:171], v[60:63], v[156:159], v[100:103]
	v_exp_f32_e32 v228, v46
	s_waitcnt lgkmcnt(8)
	v_mfma_f32_16x16x32_bf16 v[104:107], v[36:39], v[160:163], v[104:107]
	v_exp_f32_e32 v100, v47
	v_mfma_f32_16x16x32_bf16 v[160:163], v[60:63], v[160:163], v[96:99]
	v_cvt_pk_bf16_f32 v44, v2, v222
	v_cvt_pk_bf16_f32 v45, v224, v122
	v_cvt_pk_bf16_f32 v46, v226, v110
	v_cvt_pk_bf16_f32 v47, v228, v100
	v_exp_f32_e32 v96, v140
	s_waitcnt lgkmcnt(0)
	v_mfma_f32_16x16x32_bf16 v[180:183], v[36:39], v[238:241], v[88:91]
	v_exp_f32_e32 v230, v141
	v_mfma_f32_16x16x32_bf16 v[184:187], v[60:63], v[238:241], v[76:79]
	v_exp_f32_e32 v232, v142
	v_mfma_f32_16x16x32_bf16 v[80:83], v[36:39], v[242:245], v[80:83]
	v_exp_f32_e32 v78, v143
	v_mfma_f32_16x16x32_bf16 v[188:191], v[60:63], v[242:245], v[64:67]
	ds_read_b64_tr_b16 v[140:141], v215 offset:26624
	ds_read_b64_tr_b16 v[156:157], v215 offset:26656
	ds_read_b64_tr_b16 v[172:173], v215 offset:26688
	ds_read_b64_tr_b16 v[176:177], v215 offset:26720
	ds_read_b64_tr_b16 v[142:143], v215 offset:31232
	ds_read_b64_tr_b16 v[158:159], v215 offset:31264
	ds_read_b64_tr_b16 v[174:175], v215 offset:31296
	ds_read_b64_tr_b16 v[178:179], v215 offset:31328
	v_exp_f32_e32 v234, v72
	v_mfma_f32_16x16x32_bf16 v[68:71], v[36:39], v[246:249], v[68:71]
	v_exp_f32_e32 v66, v73
	v_mfma_f32_16x16x32_bf16 v[192:195], v[60:63], v[246:249], v[52:55]
	v_exp_f32_e32 v236, v74
	v_mfma_f32_16x16x32_bf16 v[56:59], v[36:39], v[250:253], v[56:59]
	v_exp_f32_e32 v54, v75
	v_mfma_f32_16x16x32_bf16 v[48:51], v[60:63], v[250:253], v[48:51]
	v_cvt_pk_bf16_f32 v72, v96, v230
	v_cvt_pk_bf16_f32 v73, v232, v78
	v_cvt_pk_bf16_f32 v74, v234, v66
	v_cvt_pk_bf16_f32 v75, v236, v54
	v_exp_f32_e32 v3, v136
	s_waitcnt lgkmcnt(0)
	v_mfma_f32_16x16x32_bf16 v[144:147], v[40:43], v[140:143], v[164:167]
	v_exp_f32_e32 v223, v137
	v_mfma_f32_16x16x32_bf16 v[140:143], v[84:87], v[140:143], v[148:151]
	ds_read_b64_tr_b16 v[238:239], v215 offset:26752
	ds_read_b64_tr_b16 v[242:243], v215 offset:26784
	ds_read_b64_tr_b16 v[246:247], v215 offset:26816
	ds_read_b64_tr_b16 v[250:251], v215 offset:26848
	ds_read_b64_tr_b16 v[240:241], v215 offset:31360
	ds_read_b64_tr_b16 v[244:245], v215 offset:31392
	ds_read_b64_tr_b16 v[248:249], v215 offset:31424
	ds_read_b64_tr_b16 v[252:253], v215 offset:31456
	v_exp_f32_e32 v225, v138
	v_mfma_f32_16x16x32_bf16 v[148:151], v[40:43], v[156:159], v[124:127]
	v_exp_f32_e32 v123, v139
	v_mfma_f32_16x16x32_bf16 v[136:139], v[84:87], v[156:159], v[152:155]
	v_exp_f32_e32 v227, v92
	v_mfma_f32_16x16x32_bf16 v[156:159], v[40:43], v[172:175], v[116:119]
	v_exp_f32_e32 v111, v93
	v_mfma_f32_16x16x32_bf16 v[152:155], v[84:87], v[172:175], v[168:171]
	v_exp_f32_e32 v229, v94
	v_mfma_f32_16x16x32_bf16 v[164:167], v[40:43], v[176:179], v[104:107]
	v_exp_f32_e32 v101, v95
	v_mfma_f32_16x16x32_bf16 v[160:163], v[84:87], v[176:179], v[160:163]
	s_nop 0
	v_cvt_pk_bf16_f32 v92, v3, v223
	v_cvt_pk_bf16_f32 v93, v225, v123
	v_cvt_pk_bf16_f32 v94, v227, v111
	v_cvt_pk_bf16_f32 v95, v229, v101
	v_exp_f32_e32 v97, v132
	s_waitcnt lgkmcnt(0)
	v_mfma_f32_16x16x32_bf16 v[172:175], v[40:43], v[238:241], v[180:183]
	v_exp_f32_e32 v231, v133
	v_mfma_f32_16x16x32_bf16 v[168:171], v[84:87], v[238:241], v[184:187]
	v_exp_f32_e32 v233, v134
	v_mfma_f32_16x16x32_bf16 v[176:179], v[40:43], v[242:245], v[80:83]
	v_exp_f32_e32 v79, v135
	v_mfma_f32_16x16x32_bf16 v[132:135], v[84:87], v[242:245], v[188:191]
	v_exp_f32_e32 v235, v112
	v_mfma_f32_16x16x32_bf16 v[184:187], v[40:43], v[246:249], v[68:71]
	v_exp_f32_e32 v67, v113
	v_mfma_f32_16x16x32_bf16 v[180:183], v[84:87], v[246:249], v[192:195]
	v_exp_f32_e32 v237, v114
	v_mfma_f32_16x16x32_bf16 v[192:195], v[40:43], v[250:253], v[56:59]
	v_exp_f32_e32 v55, v115
	v_mfma_f32_16x16x32_bf16 v[188:191], v[84:87], v[250:253], v[48:51]
	v_cvt_pk_bf16_f32 v112, v97, v231
	v_cvt_pk_bf16_f32 v113, v233, v79
	v_cvt_pk_bf16_f32 v114, v235, v67
	v_cvt_pk_bf16_f32 v115, v237, v55
	s_andn2_b64 vcc, exec, s[0:1]
	s_cbranch_vccnz .LBB0_865
	v_mov_b32_e32 v0, v210
	s_nop 0
	v_lshlrev_b32_e32 v0, 2, v0
	v_and_b32_e32 v0, 60, v0
	v_and_or_b32 v0, v212, 64, v0
	v_lshlrev_b32_e32 v0, 2, v0
	ds_bpermute_b32 v48, v0, v200
	ds_bpermute_b32 v50, v0, v200 offset:8
	ds_bpermute_b32 v51, v0, v200 offset:12
	ds_bpermute_b32 v49, v0, v200 offset:4
	ds_bpermute_b32 v56, v0, v201
	ds_bpermute_b32 v58, v0, v201 offset:8
	ds_bpermute_b32 v59, v0, v201 offset:12
	ds_bpermute_b32 v57, v0, v201 offset:4
	s_waitcnt lgkmcnt(5)
	v_pk_mul_f32 v[146:147], v[146:147], v[50:51]
	s_waitcnt lgkmcnt(4)
	v_pk_mul_f32 v[144:145], v[144:145], v[48:49]
	v_pk_mul_f32 v[150:151], v[150:151], v[50:51]
	v_pk_mul_f32 v[148:149], v[148:149], v[48:49]
	v_pk_mul_f32 v[158:159], v[158:159], v[50:51]
	v_pk_mul_f32 v[156:157], v[156:157], v[48:49]
	v_pk_mul_f32 v[166:167], v[166:167], v[50:51]
	v_pk_mul_f32 v[164:165], v[164:165], v[48:49]
	v_pk_mul_f32 v[174:175], v[174:175], v[50:51]
	v_pk_mul_f32 v[172:173], v[172:173], v[48:49]
	v_pk_mul_f32 v[178:179], v[178:179], v[50:51]
	v_pk_mul_f32 v[176:177], v[176:177], v[48:49]
	v_pk_mul_f32 v[186:187], v[186:187], v[50:51]
	v_pk_mul_f32 v[184:185], v[184:185], v[48:49]
	v_pk_mul_f32 v[194:195], v[194:195], v[50:51]
	v_pk_mul_f32 v[192:193], v[192:193], v[48:49]
	s_waitcnt lgkmcnt(1)
	v_pk_mul_f32 v[142:143], v[142:143], v[58:59]
	s_waitcnt lgkmcnt(0)
	v_pk_mul_f32 v[140:141], v[140:141], v[56:57]
	v_pk_mul_f32 v[138:139], v[138:139], v[58:59]
	v_pk_mul_f32 v[136:137], v[136:137], v[56:57]
	v_pk_mul_f32 v[154:155], v[154:155], v[58:59]
	v_pk_mul_f32 v[152:153], v[152:153], v[56:57]
	v_pk_mul_f32 v[162:163], v[162:163], v[58:59]
	v_pk_mul_f32 v[160:161], v[160:161], v[56:57]
	v_pk_mul_f32 v[170:171], v[170:171], v[58:59]
	v_pk_mul_f32 v[168:169], v[168:169], v[56:57]
	v_pk_mul_f32 v[134:135], v[134:135], v[58:59]
	v_pk_mul_f32 v[132:133], v[132:133], v[56:57]
	v_pk_mul_f32 v[182:183], v[182:183], v[58:59]
	v_pk_mul_f32 v[180:181], v[180:181], v[56:57]
	v_pk_mul_f32 v[190:191], v[190:191], v[58:59]
	v_pk_mul_f32 v[188:189], v[188:189], v[56:57]

.LBB0_877:
	v_max_f32_e32 v0, v128, v129
	v_max3_f32 v2, v131, v36, v37
	v_max3_f32 v0, v0, v130, v38
	v_max3_f32 v2, v2, v120, v121
	v_max3_f32 v0, v0, v39, v122
	v_max3_f32 v2, v2, v40, v41
	v_max3_f32 v0, v0, v123, v42
	v_max3_f32 v0, v0, v43, v2
	v_max_f32_e32 v2, v108, v109
	v_max3_f32 v3, v111, v60, v61
	v_max3_f32 v2, v2, v110, v62
	v_max3_f32 v3, v3, v64, v65
	v_max3_f32 v2, v2, v63, v66
	v_max3_f32 v3, v3, v84, v85
	v_max3_f32 v2, v2, v67, v86
	v_max3_f32 v2, v2, v87, v3
	v_max_f32_e32 v3, v0, v2
	v_cmp_lt_f32_e32 vcc, s74, v3
	s_cmp_lg_u64 vcc, 0
	s_cselect_b64 s[2:3], -1, 0
	s_cbranch_vccz .LBB0_879
	v_and_b32_e32 v124, 64, v212
	v_xor_b32_e32 v3, 16, v212
	v_add_u32_e32 v124, 64, v124
	v_cmp_lt_i32_e32 vcc, v3, v124
	v_xor_b32_e32 v125, 32, v212
	s_nop 0
	v_cndmask_b32_e32 v3, v212, v3, vcc
	v_lshlrev_b32_e32 v3, 2, v3
	ds_bpermute_b32 v126, v3, v0
	ds_bpermute_b32 v3, v3, v2
	v_cmp_lt_i32_e32 vcc, v125, v124
	v_max_f32_e32 v2, v2, v2
	v_max_f32_e32 v0, v0, v0
	v_cndmask_b32_e32 v124, v212, v125, vcc
	s_waitcnt lgkmcnt(0)
	v_max_f32_e32 v3, v3, v3
	v_lshlrev_b32_e32 v124, 2, v124
	v_max_f32_e32 v125, v126, v126
	v_max_f32_e32 v2, v2, v3
	v_max_f32_e32 v0, v0, v125
	ds_bpermute_b32 v3, v124, v2
	ds_bpermute_b32 v125, v124, v0
	s_waitcnt lgkmcnt(1)
	v_max_f32_e32 v3, v3, v3
	s_waitcnt lgkmcnt(0)
	v_max_f32_e32 v124, v125, v125
	v_max_f32_e32 v2, v2, v3
	v_max_f32_e32 v0, v0, v124
	v_cmp_lt_f32_e32 vcc, s74, v2
	s_nop 1
	v_cndmask_b32_e32 v3, 0, v2, vcc
	v_cmp_lt_f32_e32 vcc, s74, v0
	v_exp_f32_e64 v201, -v3
	v_sub_f32_e32 v108, v108, v3
	v_cndmask_b32_e32 v2, 0, v0, vcc
	v_exp_f32_e64 v200, -v2
	v_sub_f32_e32 v128, v128, v2
	v_sub_f32_e32 v129, v129, v2
	v_sub_f32_e32 v130, v130, v2
	v_sub_f32_e32 v131, v131, v2
	v_sub_f32_e32 v36, v36, v2
	v_sub_f32_e32 v37, v37, v2
	v_sub_f32_e32 v38, v38, v2
	v_sub_f32_e32 v39, v39, v2
	v_sub_f32_e32 v120, v120, v2
	v_sub_f32_e32 v121, v121, v2
	v_sub_f32_e32 v122, v122, v2
	v_sub_f32_e32 v123, v123, v2
	v_sub_f32_e32 v40, v40, v2
	v_sub_f32_e32 v41, v41, v2
	v_sub_f32_e32 v42, v42, v2
	v_sub_f32_e32 v43, v43, v2
	v_pk_add_f32 v[196:197], v[196:197], v[2:3]
	v_sub_f32_e32 v109, v109, v3
	v_sub_f32_e32 v110, v110, v3
	v_sub_f32_e32 v111, v111, v3
	v_sub_f32_e32 v60, v60, v3
	v_sub_f32_e32 v61, v61, v3
	v_sub_f32_e32 v62, v62, v3
	v_sub_f32_e32 v63, v63, v3
	v_sub_f32_e32 v64, v64, v3
	v_sub_f32_e32 v65, v65, v3
	v_sub_f32_e32 v66, v66, v3
	v_sub_f32_e32 v67, v67, v3
	v_sub_f32_e32 v84, v84, v3
	v_sub_f32_e32 v85, v85, v3
	v_sub_f32_e32 v86, v86, v3
	v_sub_f32_e32 v87, v87, v3
	v_pk_mul_f32 v[198:199], v[198:199], v[200:201]
.LBB0_879:
	ds_read_b64_tr_b16 v[124:125], v215 offset:53248
	ds_read_b64_tr_b16 v[100:101], v215 offset:53280
	ds_read_b64_tr_b16 v[116:117], v215 offset:53312
	ds_read_b64_tr_b16 v[96:97], v215 offset:53344
	ds_read_b64_tr_b16 v[126:127], v215 offset:57856
	ds_read_b64_tr_b16 v[102:103], v215 offset:57888
	ds_read_b64_tr_b16 v[118:119], v215 offset:57920
	ds_read_b64_tr_b16 v[98:99], v215 offset:57952
	v_exp_f32_e32 v2, v128
	s_waitcnt lgkmcnt(3)
	v_mfma_f32_16x16x32_bf16 v[104:107], v[44:47], v[124:127], v[144:147]
	v_exp_f32_e32 v222, v129
	v_mfma_f32_16x16x32_bf16 v[124:127], v[92:95], v[124:127], v[140:143]
	ds_read_b64_tr_b16 v[238:239], v215 offset:53376
	ds_read_b64_tr_b16 v[242:243], v215 offset:53408
	ds_read_b64_tr_b16 v[246:247], v215 offset:53440
	ds_read_b64_tr_b16 v[250:251], v215 offset:53472
	ds_read_b64_tr_b16 v[240:241], v215 offset:57984
	ds_read_b64_tr_b16 v[244:245], v215 offset:58016
	ds_read_b64_tr_b16 v[248:249], v215 offset:58048
	ds_read_b64_tr_b16 v[252:253], v215 offset:58080
	v_exp_f32_e32 v224, v130
	s_waitcnt lgkmcnt(10)
	v_mfma_f32_16x16x32_bf16 v[148:151], v[44:47], v[100:103], v[148:151]
	v_exp_f32_e32 v142, v131
	v_mfma_f32_16x16x32_bf16 v[100:103], v[92:95], v[100:103], v[136:139]
	v_exp_f32_e32 v226, v36
	s_waitcnt lgkmcnt(9)
	v_mfma_f32_16x16x32_bf16 v[156:159], v[44:47], v[116:119], v[156:159]
	v_exp_f32_e32 v138, v37
	v_mfma_f32_16x16x32_bf16 v[76:79], v[92:95], v[116:119], v[152:155]
	v_exp_f32_e32 v228, v38
	s_waitcnt lgkmcnt(8)
	v_mfma_f32_16x16x32_bf16 v[164:167], v[44:47], v[96:99], v[164:167]
	v_exp_f32_e32 v154, v39
	v_mfma_f32_16x16x32_bf16 v[96:99], v[92:95], v[96:99], v[160:163]
	v_cvt_pk_bf16_f32 v36, v2, v222
	v_cvt_pk_bf16_f32 v37, v224, v142
	v_cvt_pk_bf16_f32 v38, v226, v138
	v_cvt_pk_bf16_f32 v39, v228, v154
	v_exp_f32_e32 v160, v120
	s_waitcnt lgkmcnt(0)
	v_mfma_f32_16x16x32_bf16 v[52:55], v[44:47], v[238:241], v[172:175]
	v_exp_f32_e32 v230, v121
	v_mfma_f32_16x16x32_bf16 v[68:71], v[92:95], v[238:241], v[168:171]
	v_exp_f32_e32 v232, v122
	v_mfma_f32_16x16x32_bf16 v[176:179], v[44:47], v[242:245], v[176:179]
	v_exp_f32_e32 v170, v123
	v_mfma_f32_16x16x32_bf16 v[48:51], v[92:95], v[242:245], v[132:135]
	ds_read_b64_tr_b16 v[120:121], v215 offset:62464
	ds_read_b64_tr_b16 v[116:117], v215 offset:62496
	ds_read_b64_tr_b16 v[88:89], v215 offset:62528
	ds_read_b64_tr_b16 v[80:81], v215 offset:62560
	ds_read_b64_tr_b16 v[122:123], v216 offset:13824
	ds_read_b64_tr_b16 v[118:119], v216 offset:13856
	ds_read_b64_tr_b16 v[90:91], v216 offset:13888
	ds_read_b64_tr_b16 v[82:83], v216 offset:13920
	v_exp_f32_e32 v234, v40
	v_mfma_f32_16x16x32_bf16 v[184:187], v[44:47], v[246:249], v[184:187]
	v_exp_f32_e32 v134, v41
	v_mfma_f32_16x16x32_bf16 v[56:59], v[92:95], v[246:249], v[180:183]
	v_exp_f32_e32 v236, v42
	v_mfma_f32_16x16x32_bf16 v[192:195], v[44:47], v[250:253], v[192:195]
	v_exp_f32_e32 v182, v43
	v_mfma_f32_16x16x32_bf16 v[188:191], v[92:95], v[250:253], v[188:191]
	v_cvt_pk_bf16_f32 v40, v160, v230
	v_cvt_pk_bf16_f32 v41, v232, v170
	v_cvt_pk_bf16_f32 v42, v234, v134
	v_cvt_pk_bf16_f32 v43, v236, v182
	v_exp_f32_e32 v3, v108
	s_waitcnt lgkmcnt(0)
	v_mfma_f32_16x16x32_bf16 v[128:131], v[72:75], v[120:123], v[104:107]
	v_exp_f32_e32 v223, v109
	v_mfma_f32_16x16x32_bf16 v[120:123], v[112:115], v[120:123], v[124:127]
	ds_read_b64_tr_b16 v[238:239], v215 offset:62592
	ds_read_b64_tr_b16 v[242:243], v215 offset:62624
	ds_read_b64_tr_b16 v[246:247], v215 offset:62656
	ds_read_b64_tr_b16 v[250:251], v215 offset:62688
	ds_read_b64_tr_b16 v[240:241], v216 offset:13952
	ds_read_b64_tr_b16 v[244:245], v216 offset:13984
	ds_read_b64_tr_b16 v[248:249], v216 offset:14016
	ds_read_b64_tr_b16 v[252:253], v216 offset:14048
	v_exp_f32_e32 v225, v110
	v_mfma_f32_16x16x32_bf16 v[124:127], v[72:75], v[116:119], v[148:151]
	v_exp_f32_e32 v143, v111
	v_mfma_f32_16x16x32_bf16 v[108:111], v[112:115], v[116:119], v[100:103]
	v_exp_f32_e32 v227, v60
	v_mfma_f32_16x16x32_bf16 v[116:119], v[72:75], v[88:91], v[156:159]
	v_exp_f32_e32 v139, v61
	v_mfma_f32_16x16x32_bf16 v[100:103], v[112:115], v[88:91], v[76:79]
	v_exp_f32_e32 v229, v62
	v_mfma_f32_16x16x32_bf16 v[104:107], v[72:75], v[80:83], v[164:167]
	v_exp_f32_e32 v155, v63
	v_mfma_f32_16x16x32_bf16 v[96:99], v[112:115], v[80:83], v[96:99]
	s_nop 0
	v_cvt_pk_bf16_f32 v60, v3, v223
	v_cvt_pk_bf16_f32 v61, v225, v143
	v_cvt_pk_bf16_f32 v62, v227, v139
	v_cvt_pk_bf16_f32 v63, v229, v155
	v_exp_f32_e32 v161, v64
	s_waitcnt lgkmcnt(0)
	v_mfma_f32_16x16x32_bf16 v[88:91], v[72:75], v[238:241], v[52:55]
	v_exp_f32_e32 v231, v65
	v_mfma_f32_16x16x32_bf16 v[76:79], v[112:115], v[238:241], v[68:71]
	v_exp_f32_e32 v233, v66
	v_mfma_f32_16x16x32_bf16 v[80:83], v[72:75], v[242:245], v[176:179]
	v_exp_f32_e32 v171, v67
	v_mfma_f32_16x16x32_bf16 v[64:67], v[112:115], v[242:245], v[48:51]
	v_exp_f32_e32 v235, v84
	v_mfma_f32_16x16x32_bf16 v[68:71], v[72:75], v[246:249], v[184:187]
	v_exp_f32_e32 v135, v85
	v_mfma_f32_16x16x32_bf16 v[52:55], v[112:115], v[246:249], v[56:59]
	v_exp_f32_e32 v237, v86
	v_mfma_f32_16x16x32_bf16 v[56:59], v[72:75], v[250:253], v[192:195]
	v_exp_f32_e32 v183, v87
	v_mfma_f32_16x16x32_bf16 v[48:51], v[112:115], v[250:253], v[188:191]
	v_cvt_pk_bf16_f32 v84, v161, v231
	v_cvt_pk_bf16_f32 v85, v233, v171
	v_cvt_pk_bf16_f32 v86, v235, v135
	v_cvt_pk_bf16_f32 v87, v237, v183
	s_andn2_b64 vcc, exec, s[2:3]
	s_cbranch_vccnz .LBB0_881
	v_mov_b32_e32 v0, v210
	s_nop 0
	v_lshlrev_b32_e32 v0, 2, v0
	v_and_b32_e32 v0, 60, v0
	v_and_or_b32 v0, v212, 64, v0
	v_lshlrev_b32_e32 v0, 2, v0
	ds_bpermute_b32 v188, v0, v200
	ds_bpermute_b32 v190, v0, v200 offset:8
	ds_bpermute_b32 v191, v0, v200 offset:12
	ds_bpermute_b32 v189, v0, v200 offset:4
	ds_bpermute_b32 v192, v0, v201
	ds_bpermute_b32 v194, v0, v201 offset:8
	ds_bpermute_b32 v195, v0, v201 offset:12
	ds_bpermute_b32 v193, v0, v201 offset:4
	s_waitcnt lgkmcnt(5)
	v_pk_mul_f32 v[130:131], v[130:131], v[190:191]
	s_waitcnt lgkmcnt(4)
	v_pk_mul_f32 v[128:129], v[128:129], v[188:189]
	v_pk_mul_f32 v[126:127], v[126:127], v[190:191]
	v_pk_mul_f32 v[124:125], v[124:125], v[188:189]
	v_pk_mul_f32 v[118:119], v[118:119], v[190:191]
	v_pk_mul_f32 v[116:117], v[116:117], v[188:189]
	v_pk_mul_f32 v[106:107], v[106:107], v[190:191]
	v_pk_mul_f32 v[104:105], v[104:105], v[188:189]
	v_pk_mul_f32 v[90:91], v[90:91], v[190:191]
	v_pk_mul_f32 v[88:89], v[88:89], v[188:189]
	v_pk_mul_f32 v[82:83], v[82:83], v[190:191]
	v_pk_mul_f32 v[80:81], v[80:81], v[188:189]
	v_pk_mul_f32 v[70:71], v[70:71], v[190:191]
	v_pk_mul_f32 v[68:69], v[68:69], v[188:189]
	v_pk_mul_f32 v[58:59], v[58:59], v[190:191]
	v_pk_mul_f32 v[56:57], v[56:57], v[188:189]
	s_waitcnt lgkmcnt(1)
	v_pk_mul_f32 v[122:123], v[122:123], v[194:195]
	s_waitcnt lgkmcnt(0)
	v_pk_mul_f32 v[120:121], v[120:121], v[192:193]
	v_pk_mul_f32 v[110:111], v[110:111], v[194:195]
	v_pk_mul_f32 v[108:109], v[108:109], v[192:193]
	v_pk_mul_f32 v[102:103], v[102:103], v[194:195]
	v_pk_mul_f32 v[100:101], v[100:101], v[192:193]
	v_pk_mul_f32 v[98:99], v[98:99], v[194:195]
	v_pk_mul_f32 v[96:97], v[96:97], v[192:193]
	v_pk_mul_f32 v[78:79], v[78:79], v[194:195]
	v_pk_mul_f32 v[76:77], v[76:77], v[192:193]
	v_pk_mul_f32 v[66:67], v[66:67], v[194:195]
	v_pk_mul_f32 v[64:65], v[64:65], v[192:193]
	v_pk_mul_f32 v[54:55], v[54:55], v[194:195]
	v_pk_mul_f32 v[52:53], v[52:53], v[192:193]
	v_pk_mul_f32 v[50:51], v[50:51], v[194:195]
	v_pk_mul_f32 v[48:49], v[48:49], v[192:193]

.LBB0_927:
	v_max_f32_e32 v0, v144, v145
	v_max3_f32 v2, v147, v44, v45
	v_max3_f32 v0, v0, v146, v46
	v_max3_f32 v2, v2, v140, v141
	v_max3_f32 v0, v0, v47, v142
	v_max3_f32 v2, v2, v56, v57
	v_max3_f32 v0, v0, v143, v58
	v_max3_f32 v0, v0, v59, v2
	v_max_f32_e32 v2, v136, v137
	v_max3_f32 v3, v139, v88, v89
	v_max3_f32 v2, v2, v138, v90
	v_max3_f32 v3, v3, v132, v133
	v_max3_f32 v2, v2, v91, v134
	v_max3_f32 v3, v3, v96, v97
	v_max3_f32 v2, v2, v135, v98
	v_max3_f32 v2, v2, v99, v3
	v_max_f32_e32 v3, v0, v2
	v_cmp_lt_f32_e32 vcc, s74, v3
	s_cmp_lg_u64 vcc, 0
	s_cselect_b64 s[0:1], -1, 0
	s_cbranch_vccz .LBB0_929
	ds_bpermute_b32 v148, v217, v2
	ds_bpermute_b32 v3, v217, v0
	v_max_f32_e32 v2, v2, v2
	v_max_f32_e32 v0, v0, v0
	s_waitcnt lgkmcnt(1)
	v_max_f32_e32 v148, v148, v148
	s_waitcnt lgkmcnt(0)
	v_max_f32_e32 v3, v3, v3
	v_max_f32_e32 v2, v2, v148
	v_max_f32_e32 v0, v0, v3
	ds_bpermute_b32 v148, v216, v2
	ds_bpermute_b32 v3, v216, v0
	s_waitcnt lgkmcnt(1)
	v_max_f32_e32 v148, v148, v148
	s_waitcnt lgkmcnt(0)
	v_max_f32_e32 v3, v3, v3
	v_max_f32_e32 v2, v2, v148
	v_max_f32_e32 v0, v0, v3
	v_cmp_lt_f32_e32 vcc, s74, v2
	s_nop 1
	v_cndmask_b32_e32 v3, 0, v2, vcc
	v_cmp_lt_f32_e32 vcc, s74, v0
	v_exp_f32_e64 v199, -v3
	v_sub_f32_e32 v136, v136, v3
	v_cndmask_b32_e32 v2, 0, v0, vcc
	v_exp_f32_e64 v198, -v2
	v_sub_f32_e32 v144, v144, v2
	v_sub_f32_e32 v145, v145, v2
	v_sub_f32_e32 v146, v146, v2
	v_sub_f32_e32 v147, v147, v2
	v_sub_f32_e32 v44, v44, v2
	v_sub_f32_e32 v45, v45, v2
	v_sub_f32_e32 v46, v46, v2
	v_sub_f32_e32 v47, v47, v2
	v_sub_f32_e32 v140, v140, v2
	v_sub_f32_e32 v141, v141, v2
	v_sub_f32_e32 v142, v142, v2
	v_sub_f32_e32 v143, v143, v2
	v_sub_f32_e32 v56, v56, v2
	v_sub_f32_e32 v57, v57, v2
	v_sub_f32_e32 v58, v58, v2
	v_sub_f32_e32 v59, v59, v2
	v_pk_add_f32 v[196:197], v[196:197], v[2:3]
	v_sub_f32_e32 v137, v137, v3
	v_sub_f32_e32 v138, v138, v3
	v_sub_f32_e32 v139, v139, v3
	v_sub_f32_e32 v88, v88, v3
	v_sub_f32_e32 v89, v89, v3
	v_sub_f32_e32 v90, v90, v3
	v_sub_f32_e32 v91, v91, v3
	v_sub_f32_e32 v132, v132, v3
	v_sub_f32_e32 v133, v133, v3
	v_sub_f32_e32 v134, v134, v3
	v_sub_f32_e32 v135, v135, v3
	v_sub_f32_e32 v96, v96, v3
	v_sub_f32_e32 v97, v97, v3
	v_sub_f32_e32 v98, v98, v3
	v_sub_f32_e32 v99, v99, v3
	v_pk_mul_f32 v[200:201], v[200:201], v[198:199]

.LBB0_943:
	v_max_f32_e32 v0, v128, v129
	v_max3_f32 v2, v131, v36, v37
	v_max3_f32 v0, v0, v130, v38
	v_max3_f32 v2, v2, v124, v125
	v_max3_f32 v0, v0, v39, v126
	v_max3_f32 v2, v2, v40, v41
	v_max3_f32 v0, v0, v127, v42
	v_max3_f32 v0, v0, v43, v2
	v_max_f32_e32 v2, v116, v117
	v_max3_f32 v3, v119, v48, v49
	v_max3_f32 v2, v2, v118, v50
	v_max3_f32 v3, v3, v72, v73
	v_max3_f32 v2, v2, v51, v74
	v_max3_f32 v3, v3, v76, v77
	v_max3_f32 v2, v2, v75, v78
	v_max3_f32 v2, v2, v79, v3
	v_max_f32_e32 v3, v0, v2
	v_cmp_lt_f32_e32 vcc, s74, v3
	s_cmp_lg_u64 vcc, 0
	s_cselect_b64 s[2:3], -1, 0
	s_cbranch_vccz .LBB0_945
	ds_bpermute_b32 v120, v217, v2
	ds_bpermute_b32 v3, v217, v0
	v_max_f32_e32 v2, v2, v2
	v_max_f32_e32 v0, v0, v0
	s_waitcnt lgkmcnt(1)
	v_max_f32_e32 v120, v120, v120
	s_waitcnt lgkmcnt(0)
	v_max_f32_e32 v3, v3, v3
	v_max_f32_e32 v2, v2, v120
	v_max_f32_e32 v0, v0, v3
	ds_bpermute_b32 v120, v216, v2
	ds_bpermute_b32 v3, v216, v0
	s_waitcnt lgkmcnt(1)
	v_max_f32_e32 v120, v120, v120
	s_waitcnt lgkmcnt(0)
	v_max_f32_e32 v3, v3, v3
	v_max_f32_e32 v2, v2, v120
	v_max_f32_e32 v0, v0, v3
	v_cmp_lt_f32_e32 vcc, s74, v2
	s_nop 1
	v_cndmask_b32_e32 v3, 0, v2, vcc
	v_cmp_lt_f32_e32 vcc, s74, v0
	v_exp_f32_e64 v199, -v3
	v_sub_f32_e32 v116, v116, v3
	v_cndmask_b32_e32 v2, 0, v0, vcc
	v_exp_f32_e64 v198, -v2
	v_sub_f32_e32 v128, v128, v2
	v_sub_f32_e32 v129, v129, v2
	v_sub_f32_e32 v130, v130, v2
	v_sub_f32_e32 v131, v131, v2
	v_sub_f32_e32 v36, v36, v2
	v_sub_f32_e32 v37, v37, v2
	v_sub_f32_e32 v38, v38, v2
	v_sub_f32_e32 v39, v39, v2
	v_sub_f32_e32 v124, v124, v2
	v_sub_f32_e32 v125, v125, v2
	v_sub_f32_e32 v126, v126, v2
	v_sub_f32_e32 v127, v127, v2
	v_sub_f32_e32 v40, v40, v2
	v_sub_f32_e32 v41, v41, v2
	v_sub_f32_e32 v42, v42, v2
	v_sub_f32_e32 v43, v43, v2
	v_pk_add_f32 v[196:197], v[196:197], v[2:3]
	v_sub_f32_e32 v117, v117, v3
	v_sub_f32_e32 v118, v118, v3
	v_sub_f32_e32 v119, v119, v3
	v_sub_f32_e32 v48, v48, v3
	v_sub_f32_e32 v49, v49, v3
	v_sub_f32_e32 v50, v50, v3
	v_sub_f32_e32 v51, v51, v3
	v_sub_f32_e32 v72, v72, v3
	v_sub_f32_e32 v73, v73, v3
	v_sub_f32_e32 v74, v74, v3
	v_sub_f32_e32 v75, v75, v3
	v_sub_f32_e32 v76, v76, v3
	v_sub_f32_e32 v77, v77, v3
	v_sub_f32_e32 v78, v78, v3
	v_sub_f32_e32 v79, v79, v3
	v_pk_mul_f32 v[200:201], v[200:201], v[198:199]
